# v20 plus back-edge rotation: loop tail is one taken conditional branch instead of not-taken branch plus s_mov plus s_branch
# baseline (speedup 1.0000x reference)
; template <int DQK, int MODE, bool PIPE>
; DI void attn_core(const u16* __restrict__ Qg, const u16* __restrict__ Kg, const u16* __restrict__ Vtg, int ntiles,
;                   int kr_lo, int rs, int r_q, int c_q, int cs, const float* biasL, char* lds, f32x16 (&o)[4], float& l_out, int tid) {
;     ...
;   auto gloadK = [&](int t) {
;     const u16* kp = Kg + (size_t)keystart(t) * DQK;
; #pragma unroll
;     for (int j = 0; j < KPT; ++j) rk[j] = *(const u32x4*)(kp + (size_t)(tid + NT_ * j) * 8);
;   };
;   auto gloadV = [&](int t) {
;     const int key0 = keystart(t);
; #pragma unroll
;     for (int j = 0; j < 2; ++j) { const int q = tid + NT_ * j; rv[j] = *(const u32x4*)(Vtg + (size_t)(q >> 3) * NR + key0 + (q & 7) * 8); }
;   };
;   auto swriteK = [&](int b) {
;     char* base = lds + b * A_BUF;
; #pragma unroll
;     for (int j = 0; j < KPT; ++j) { const int q = tid + NT_ * j; const int row = q / NKP, pcs = q - row * NKP;
;       *(u32x4*)(base + row * KSTR + pcs * 16) = rk[j]; }
;   };
;   auto swriteV = [&](int b) {
;     char* base = lds + b * A_BUF;
; #pragma unroll
;     for (int j = 0; j < 2; ++j) { const int q = tid + NT_ * j; char* d = base + A_VOFF + (q >> 3) * 136 + (q & 7) * 16;
;       u32x2 lo = {rv[j][0], rv[j][1]}, hi = {rv[j][2], rv[j][3]};
;       *(u32x2*)d = lo; *(u32x2*)(d + 8) = hi; }
;   };
;     ...
;       const int j = it - N_DIFF, hd = j / 65, qb = j % 65, q0 = qb * 256, nt = qb == 0 ? 4 : NR / 64;
;       attn_core<192, 0, false>(p.Qmla + ((size_t)hd * NR + q0) * 192, p.Kmla + (size_t)hd * NR * 192, p.VtMla + (size_t)hd * 128 * NR, nt, 0, 0, 0, 0, 0, biasL, lds, o, l, tid);
.LBB0_815:
	s_and_b64 vcc, exec, s[0:1]
	s_cbranch_vccz .LBB0_832
	s_add_i32 s0, s67, 0xfebb
	s_and_b32 s1, s0, 0xffff
	s_mulk_i32 s1, 0xfc1
	s_lshr_b32 s12, s1, 18
	s_mul_i32 s1, s12, 0x41
	s_sub_i32 s0, s0, s1
	s_lshl_b32 s16, s0, 8
	s_and_b32 s0, s0, 0xffff
	s_cmp_eq_u32 s0, 0
	s_cselect_b32 s17, 4, 0x104
	s_mul_i32 s0, s12, 0x4100
	s_and_b32 s1, s16, 0xff00
	s_add_i32 s0, s0, s1
	v_readlane_b32 s76, v252, 62
	s_mul_hi_u32 s1, s0, 0x180
	s_mulk_i32 s0, 0x180
	v_readlane_b32 s82, v253, 4
	v_readlane_b32 s83, v253, 5
	s_add_u32 s6, s82, s0
	v_readlane_b32 s84, v253, 6
	s_addc_u32 s7, s83, s1
	s_mul_i32 s0, s12, 0x618000
	v_readlane_b32 s85, v253, 7
	s_mul_hi_u32 s1, s12, 0x618000
	s_add_u32 s0, s84, s0
	v_ashrrev_i32_e32 v217, 31, v216
	s_addc_u32 s1, s85, s1
	v_lshlrev_b64 v[22:23], 4, v[216:217]
	v_lshl_add_u64 v[2:3], s[0:1], 0, v[22:23]
	global_load_dwordx4 v[2:5], v[2:3], off
	v_add_u32_e32 v24, 0x200, v216
	v_readlane_b32 s86, v253, 8
	s_mul_i32 s8, s12, 0x410000
	v_ashrrev_i32_e32 v25, 31, v24
	v_readlane_b32 s87, v253, 9
	s_mul_hi_u32 s9, s12, 0x410000
	s_add_u32 s8, s86, s8
	v_lshlrev_b64 v[26:27], 4, v[24:25]
	v_add_u32_e32 v28, 0x400, v216
	s_addc_u32 s9, s87, s9
	v_lshl_add_u64 v[6:7], s[0:1], 0, v[26:27]
	v_ashrrev_i32_e32 v29, 31, v28
	global_load_dwordx4 v[6:9], v[6:7], off
	v_lshlrev_b64 v[30:31], 4, v[28:29]
	v_ashrrev_i32_e32 v25, 3, v216
	v_mov_b64_e32 v[18:19], s[8:9]
	s_mov_b32 s10, 0x8200
	v_ashrrev_i32_e32 v29, 3, v24
	v_mad_i64_i32 v[14:15], s[8:9], v25, s10, v[18:19]
	v_lshlrev_b32_e32 v0, 4, v216
	v_mad_i64_i32 v[18:19], s[8:9], v29, s10, v[18:19]
	v_and_b32_e32 v166, 0x70, v0
	v_ashrrev_i32_e32 v0, 1, v216
	s_movk_i32 s8, 0xffe0
	v_and_or_b32 v0, v0, s8, v193
	v_mov_b64_e32 v[36:37], s[6:7]
	v_mov_b32_e32 v167, v1
	v_mad_i64_i32 v[36:37], s[6:7], v0, s50, v[36:37]
	v_lshlrev_b32_e32 v0, 4, v195
	v_lshl_add_u64 v[10:11], s[0:1], 0, v[30:31]
	v_lshl_add_u64 v[32:33], v[14:15], 0, v[166:167]
	v_lshl_add_u64 v[34:35], v[18:19], 0, v[166:167]
	v_lshl_add_u64 v[36:37], v[36:37], 0, v[0:1]
	global_load_dwordx4 v[10:13], v[10:11], off
	s_add_u32 s6, s0, 0x6000
	global_load_dwordx4 v[14:17], v[32:33], off
	global_load_dwordx4 v[18:21], v[34:35], off
	global_load_dwordx4 v[98:101], v[36:37], off
	global_load_dwordx4 v[102:105], v[36:37], off offset:32
	global_load_dwordx4 v[106:109], v[36:37], off offset:64
	global_load_dwordx4 v[110:113], v[36:37], off offset:96
	global_load_dwordx4 v[114:117], v[36:37], off offset:128
	global_load_dwordx4 v[118:121], v[36:37], off offset:160
	global_load_dwordx4 v[122:125], v[36:37], off offset:192
	global_load_dwordx4 v[126:129], v[36:37], off offset:224
	global_load_dwordx4 v[130:133], v[36:37], off offset:256
	global_load_dwordx4 v[134:137], v[36:37], off offset:288
	global_load_dwordx4 v[138:141], v[36:37], off offset:320
	global_load_dwordx4 v[142:145], v[36:37], off offset:352
	s_addc_u32 s7, s1, 0
	v_lshl_add_u64 v[36:37], s[6:7], 0, v[22:23]
	v_lshl_add_u64 v[38:39], s[6:7], 0, v[26:27]
	global_load_dwordx4 v[146:149], v[36:37], off
	global_load_dwordx4 v[154:157], v[38:39], off
	v_lshl_add_u64 v[36:37], s[6:7], 0, v[30:31]
	global_load_dwordx4 v[162:165], v[36:37], off
	global_load_dwordx4 v[150:153], v[32:33], off offset:128
	global_load_dwordx4 v[158:161], v[34:35], off offset:128
	s_mov_b32 s7, 0x2aaaaaab
	v_mul_hi_i32 v34, v216, s7
	v_mad_i64_i32 v[32:33], s[8:9], v25, s10, 0
	v_lshrrev_b32_e32 v36, 31, v34
	v_ashrrev_i32_e32 v37, 2, v34
	v_mad_i64_i32 v[34:35], s[8:9], v29, s10, 0
	v_add_u32_e32 v36, v37, v36
	s_movk_i32 s8, 0xffe8
	v_mul_lo_u32 v37, v36, s8
	s_movk_i32 s9, 0x190
	v_mul_lo_u32 v167, v36, s9
	v_add_lshl_u32 v169, v37, v216, 4
	v_add3_u32 v36, 0, v167, v169
	v_readlane_b32 s10, v254, 30
	v_readlane_b32 s11, v254, 31
	s_mov_b32 s6, 0
	v_lshlrev_b32_e32 v168, 3, v195
	s_mov_b32 s53, 0x8200
	v_mul_u32_u24_e32 v225, 0x190, v193
	v_mul_u32_u24_e32 v226, 0x88, v193
	v_mov_b32_e32 v222, 0
	v_mov_b32_e32 v227, 0
	v_readlane_b32 s77, v252, 63
	v_readlane_b32 s78, v253, 0
	v_readlane_b32 s79, v253, 1
	v_readlane_b32 s80, v253, 2
	v_readlane_b32 s81, v253, 3
	v_readlane_b32 s88, v253, 10
	v_readlane_b32 s89, v253, 11
	v_readlane_b32 s90, v253, 12
	s_waitcnt vmcnt(21)
	ds_write_b128 v36, v[2:5]
	v_mul_hi_i32 v2, v24, s7
	v_lshrrev_b32_e32 v3, 31, v2
	v_ashrrev_i32_e32 v2, 2, v2
	v_add_u32_e32 v2, v2, v3
	v_mul_lo_u32 v3, v2, s8
	v_mul_lo_u32 v199, v2, s9
	v_add_lshl_u32 v217, v3, v24, 4
	v_add3_u32 v2, 0, v199, v217
	v_mov_b32_e32 v4, v1
	v_mov_b32_e32 v5, v1
	v_readlane_b32 s91, v253, 13
	s_waitcnt vmcnt(20)
	ds_write_b128 v2, v[6:9]
	v_mul_hi_i32 v2, v28, s7
	v_lshrrev_b32_e32 v3, 31, v2
	v_ashrrev_i32_e32 v2, 2, v2
	v_add_u32_e32 v2, v2, v3
	v_mul_lo_u32 v3, v2, s8
	v_mul_lo_u32 v220, v2, s9
	v_add_lshl_u32 v221, v3, v28, 4
	s_movk_i32 s7, 0x88
	v_add3_u32 v2, 0, v220, v221
	v_mul_lo_u32 v223, v25, s7
	v_mul_lo_u32 v224, v29, s7
	s_mov_b64 s[8:9], 0xc000
	v_lshl_add_u64 v[170:171], v[22:23], 0, s[8:9]
	v_lshl_add_u64 v[172:173], v[26:27], 0, s[8:9]
	v_lshl_add_u64 v[174:175], v[30:31], 0, s[8:9]
	v_mov_b32_e32 v6, v1
	v_mov_b32_e32 v7, v1
	v_mov_b32_e32 v8, v1
	v_mov_b32_e32 v9, v1
	s_waitcnt vmcnt(19)
	ds_write_b128 v2, v[10:13]
	v_add_u32_e32 v2, 0, v223
	v_add3_u32 v2, v2, v166, s33
	s_waitcnt vmcnt(18)
	ds_write2_b64 v2, v[14:15], v[16:17] offset1:1
	v_add_u32_e32 v2, 0, v224
	v_add3_u32 v2, v2, v166, s33
	s_waitcnt vmcnt(17)
	ds_write2_b64 v2, v[18:19], v[20:21] offset1:1
	v_mad_u64_u32 v[2:3], s[8:9], s12, v191, v[32:33]
	v_or_b32_e32 v2, v2, v166
	v_lshl_add_u64 v[176:177], s[10:11], 0, v[2:3]
	v_mad_u64_u32 v[2:3], s[8:9], s12, v191, v[34:35]
	v_or_b32_e32 v2, v2, v166
	v_mov_b32_e32 v16, v1
	v_mov_b32_e32 v17, v1
	v_lshl_add_u64 v[218:219], s[10:11], 0, v[2:3]
	v_mov_b32_e32 v2, v1
	v_mov_b32_e32 v3, v1
	v_mov_b32_e32 v10, v1
	v_mov_b32_e32 v11, v1
	v_mov_b32_e32 v12, v1
	v_mov_b32_e32 v13, v1
	v_mov_b32_e32 v14, v1
	v_mov_b32_e32 v15, v1
	v_mov_b64_e32 v[32:33], v[16:17]
	v_mov_b64_e32 v[48:49], v[16:17]
	v_mov_b64_e32 v[64:65], v[16:17]
	v_mov_b64_e32 v[30:31], v[14:15]
	v_mov_b64_e32 v[28:29], v[12:13]
	v_mov_b64_e32 v[26:27], v[10:11]
	v_mov_b64_e32 v[24:25], v[8:9]
	v_mov_b64_e32 v[22:23], v[6:7]
	v_mov_b64_e32 v[20:21], v[4:5]
	v_mov_b64_e32 v[18:19], v[2:3]
	v_mov_b64_e32 v[46:47], v[14:15]
	v_mov_b64_e32 v[44:45], v[12:13]
	v_mov_b64_e32 v[42:43], v[10:11]
	v_mov_b64_e32 v[40:41], v[8:9]
	v_mov_b64_e32 v[38:39], v[6:7]
	v_mov_b64_e32 v[36:37], v[4:5]
	v_mov_b64_e32 v[34:35], v[2:3]
	v_mov_b64_e32 v[62:63], v[14:15]
	v_mov_b64_e32 v[60:61], v[12:13]
	v_mov_b64_e32 v[58:59], v[10:11]
	v_mov_b64_e32 v[56:57], v[8:9]
	v_mov_b64_e32 v[54:55], v[6:7]
	v_mov_b64_e32 v[52:53], v[4:5]
	v_mov_b64_e32 v[50:51], v[2:3]
	s_waitcnt vmcnt(0) lgkmcnt(0)
	s_barrier
	s_branch .LBB0_817
.Lmy_back_ml:
	s_mov_b32 s6, s18

; template <int DQK, int MODE, bool PIPE>
; DI void attn_core(const u16* __restrict__ Qg, const u16* __restrict__ Kg, const u16* __restrict__ Vtg, int ntiles,
;                   int kr_lo, int rs, int r_q, int c_q, int cs, const float* biasL, char* lds, f32x16 (&o)[4], float& l_out, int tid) {
;     ...
;     for (int i = 0; i < 16; ++i) { p0[i] = __builtin_amdgcn_exp2f(p0[i]); p1[i] = __builtin_amdgcn_exp2f(p1[i]); ps += p0[i] + p1[i]; }
;     l += ps;
;     ...
;     __syncthreads();
;     ...
;     for (int t = 0; t < ntiles; ++t) step(t, a0, a1, a0, a1);
.LBB0_829:
	v_pk_add_f32 v[250:251], v[66:67], v[82:83]
	v_pk_add_f32 v[250:251], v[250:251], v[68:69]
	v_pk_add_f32 v[250:251], v[250:251], v[70:71]
	v_pk_add_f32 v[250:251], v[250:251], v[72:73]
	v_pk_add_f32 v[250:251], v[250:251], v[74:75]
	v_pk_add_f32 v[250:251], v[250:251], v[76:77]
	v_pk_add_f32 v[250:251], v[250:251], v[78:79]
	v_pk_add_f32 v[250:251], v[250:251], v[80:81]
	v_pk_add_f32 v[250:251], v[250:251], v[84:85]
	v_pk_add_f32 v[250:251], v[250:251], v[86:87]
	v_pk_add_f32 v[250:251], v[250:251], v[88:89]
	v_pk_add_f32 v[250:251], v[250:251], v[90:91]
	v_pk_add_f32 v[250:251], v[250:251], v[92:93]
	v_pk_add_f32 v[250:251], v[250:251], v[94:95]
	v_pk_add_f32 v[250:251], v[250:251], v[96:97]
	v_add_f32_e32 v222, v222, v250
	v_add_f32_e32 v222, v222, v251
	s_add_u32 s0, s0, 0x6000
	s_addc_u32 s1, s1, 0
	v_lshl_add_u64 v[176:177], v[176:177], 0, s[2:3]
	s_cmp_lg_u32 s17, s18
	v_lshl_add_u64 v[218:219], v[218:219], 0, s[2:3]
	s_waitcnt lgkmcnt(0)
	s_barrier
	s_cbranch_scc1 .Lmy_back_ml

; #define SBAR() __builtin_amdgcn_sched_barrier(0)
; template <int DQK, int MODE, bool PIPE>
; DI void attn_core(const u16* __restrict__ Qg, const u16* __restrict__ Kg, const u16* __restrict__ Vtg, int ntiles,
;                   int kr_lo, int rs, int r_q, int c_q, int cs, const float* biasL, char* lds, f32x16 (&o)[4], float& l_out, int tid) {
;     ...
;     for (int i = 0; i < 16; ++i) { p0[i] = __builtin_amdgcn_exp2f(p0[i]); p1[i] = __builtin_amdgcn_exp2f(p1[i]); ps += p0[i] + p1[i]; }
;     l += ps;
;     const char* vb = lds + (t & 1) * A_BUF + A_VOFF + r32 * 136 + h * 8;
;     {
;       bf16x8 pfc;
;       constexpr int R = PV_RING;
;       const unsigned vaddr = (unsigned)(size_t)vb;
;       s16x4 vlo[R], vhi[R];
;       SBAR();
;       vlo[0] = lds_rd64<0>(vaddr); vhi[0] = lds_rd64<16>(vaddr);
;       vlo[1] = lds_rd64<32 * 136>(vaddr); vhi[1] = lds_rd64<32 * 136 + 16>(vaddr);
;       if (R > 2) { vlo[2 % R] = lds_rd64<64 * 136>(vaddr); vhi[2 % R] = lds_rd64<64 * 136 + 16>(vaddr); }
;       if (R > 3) { vlo[3 % R] = lds_rd64<96 * 136>(vaddr); vhi[3 % R] = lds_rd64<96 * 136 + 16>(vaddr); }
;       SBAR();
;       __builtin_amdgcn_s_setprio(1);
;       PvStep<0, 16, R>::run(vaddr, vlo, vhi, p0, p1, pfc, o);
.LBB0_837:
	v_exp_f32_e32 v52, v20
	v_exp_f32_e32 v146, v36
	v_exp_f32_e32 v53, v21
	v_exp_f32_e32 v147, v37
	v_exp_f32_e32 v54, v22
	v_exp_f32_e32 v148, v38
	v_exp_f32_e32 v55, v23
	v_exp_f32_e32 v149, v39
	v_add_f32_e32 v20, v146, v52
	v_add_f32_e32 v20, 0, v20
	v_add_f32_e32 v21, v147, v53
	v_add_f32_e32 v20, v21, v20
	v_add_f32_e32 v21, v148, v54
	v_add_f32_e32 v20, v21, v20
	v_add_f32_e32 v21, v149, v55
	v_add_f32_e32 v36, v21, v20
	v_exp_f32_e32 v21, v24
	v_exp_f32_e32 v23, v40
	v_exp_f32_e32 v20, v25
	v_exp_f32_e32 v22, v41
	v_lshlrev_b32_e32 v166, 3, v195
	s_cmp_eq_u32 s10, 0
	v_mad_i64_i32 v[90:91], s[14:15], v3, s16, 0
	v_pk_add_f32 v[24:25], v[22:23], v[20:21]
	s_mov_b32 s53, 0x8200
	v_add_f32_e32 v25, v25, v36
	v_pk_mov_b32 v[36:37], v[20:21], v[20:21] op_sel:[1,0]
	v_pk_mov_b32 v[20:21], v[22:23], v[22:23] op_sel:[1,0]
	v_add_f32_e32 v38, v24, v25
	v_exp_f32_e32 v23, v26
	v_exp_f32_e32 v25, v42
	v_exp_f32_e32 v22, v27
	v_exp_f32_e32 v24, v43
	v_mad_i64_i32 v[88:89], s[14:15], v4, s16, 0
	v_mul_u32_u24_e32 v167, 0x90, v193
	v_pk_add_f32 v[26:27], v[24:25], v[22:23]
	s_cselect_b32 s10, 4, 0x104
	v_add_f32_e32 v27, v27, v38
	v_pk_mov_b32 v[38:39], v[22:23], v[22:23] op_sel:[1,0]
	v_add_f32_e32 v40, v26, v27
	v_exp_f32_e32 v23, v28
	v_exp_f32_e32 v27, v44
	v_exp_f32_e32 v22, v29
	v_exp_f32_e32 v26, v45
	v_mul_u32_u24_e32 v168, 0x88, v193
	v_mov_b32_e32 v3, v2
	v_pk_mov_b32 v[108:109], v[22:23], v[22:23] op_sel:[1,0]
	v_pk_add_f32 v[28:29], v[26:27], v[22:23]
	v_pk_mov_b32 v[22:23], v[26:27], v[26:27] op_sel:[1,0]
	v_add_f32_e32 v29, v29, v40
	v_add_f32_e32 v40, v28, v29
	v_exp_f32_e32 v27, v30
	v_exp_f32_e32 v29, v46
	v_exp_f32_e32 v26, v31
	v_exp_f32_e32 v28, v47
	v_mov_b32_e32 v4, v2
	v_mov_b32_e32 v5, v2
	v_pk_mov_b32 v[110:111], v[26:27], v[26:27] op_sel:[1,0]
	v_pk_add_f32 v[30:31], v[28:29], v[26:27]
	v_pk_mov_b32 v[26:27], v[28:29], v[28:29] op_sel:[1,0]
	v_add_f32_e32 v31, v31, v40
	v_add_f32_e32 v40, v30, v31
	v_exp_f32_e32 v29, v32
	v_exp_f32_e32 v31, v48
	v_exp_f32_e32 v28, v33
	v_exp_f32_e32 v30, v49
	v_mov_b32_e32 v6, v2
	v_mov_b32_e32 v7, v2
	v_pk_mov_b32 v[112:113], v[28:29], v[28:29] op_sel:[1,0]
	v_pk_add_f32 v[32:33], v[30:31], v[28:29]
	v_pk_mov_b32 v[138:139], v[30:31], v[30:31] op_sel:[1,0]
	v_exp_f32_e32 v29, v34
	v_exp_f32_e32 v31, v50
	v_exp_f32_e32 v28, v35
	v_exp_f32_e32 v30, v51
	v_add_f32_e32 v33, v33, v40
	v_add_f32_e32 v40, v32, v33
	v_pk_mov_b32 v[140:141], v[28:29], v[28:29] op_sel:[1,0]
	v_pk_add_f32 v[32:33], v[30:31], v[28:29]
	v_mov_b32_e32 v8, v2
	v_add_f32_e32 v33, v33, v40
	v_add_f32_e32 v28, v32, v33
	v_add_f32_e32 v176, v2, v28
	v_lshlrev_b32_e32 v28, 3, v193
	v_sub_u32_e32 v19, v19, v28
	v_mov_b32_e32 v9, v2
	v_mov_b32_e32 v10, v2
	v_mov_b32_e32 v11, v2
	v_mov_b32_e32 v12, v2
	v_mov_b32_e32 v13, v2
	v_mov_b32_e32 v14, v2
	v_mov_b32_e32 v15, v2
	v_mov_b32_e32 v16, v2
	v_mov_b32_e32 v17, v2
	v_pk_mov_b32 v[24:25], v[24:25], v[24:25] op_sel:[1,0]
	v_pk_mov_b32 v[144:145], v[30:31], v[30:31] op_sel:[1,0]
	v_add3_u32 v169, v19, v166, s33
	ds_read_b64 v[28:29], v169 offset:0
	ds_read_b64 v[30:31], v169 offset:16
	ds_read_b64 v[32:33], v169 offset:0x1100
	ds_read_b64 v[34:35], v169 offset:0x1110
	ds_read_b64 v[92:93], v169 offset:0x2200
	ds_read_b64 v[94:95], v169 offset:0x2210
	ds_read_b64 v[96:97], v169 offset:0x3300
	ds_read_b64 v[98:99], v169 offset:0x3310
	s_setprio 1
	s_waitcnt lgkmcnt(6)
	v_cvt_pk_bf16_f32 v100, v52, v53
	v_cvt_pk_bf16_f32 v101, v54, v55
	v_cvt_pk_bf16_f32 v102, v36, v37
	v_cvt_pk_bf16_f32 v103, v38, v39
	s_nop 1
	v_mfma_f32_32x32x16_bf16 v[66:81], v[28:31], v[100:103], v[2:17]
	ds_read_b64 v[28:29], v169 offset:32
	ds_read_b64 v[30:31], v169 offset:48
	s_waitcnt lgkmcnt(6)
	v_mfma_f32_32x32x16_bf16 v[50:65], v[32:35], v[100:103], v[2:17]
	ds_read_b64 v[104:105], v169 offset:0x1120
	ds_read_b64 v[106:107], v169 offset:0x1130
	s_waitcnt lgkmcnt(6)
; #define MFMA(a, b, c) __builtin_amdgcn_mfma_f32_32x32x16_bf16((a), (b), (c), 0, 0, 0)
; template <int N> DI void lgkm_wait() { asm volatile("s_waitcnt lgkmcnt(%0)" :: "i"(N) : "memory"); }
; #define SBAR() __builtin_amdgcn_sched_barrier(0)
;   static DI void run(unsigned vaddr, s16x4 (&lo)[R], s16x4 (&hi)[R], const f32x16& p0, const f32x16& p1, bf16x8& pfc, f32x16 (&o)[4]) {
;     constexpr int issued = (J + R < NF) ? (J + R) : NF;
;     if constexpr ((J & 3) == 0) {
;       if constexpr ((J >> 2) == 0) pfc = pack8<0>(p0);
;       else if constexpr ((J >> 2) == 1) pfc = pack8<8>(p0);
;       else if constexpr ((J >> 2) == 2) pfc = pack8<0>(p1);
;       else pfc = pack8<8>(p1);
;     }
;     lgkm_wait<2 * (issued - J - 1)>(); SBAR();
;     o[J & 3] = MFMA(__builtin_shufflevector(lo[J % R], hi[J % R], 0, 1, 2, 3, 4, 5, 6, 7), pfc, o[J & 3]);
;     SBAR();
;     if (J + R < NF) {
;       constexpr int off = ((J + R) & 3) * 32 * 136 + ((J + R) >> 2) * 32;
;       lo[J % R] = lds_rd64<off>(vaddr); hi[J % R] = lds_rd64<off + 16>(vaddr); SBAR();
;     }
;     if constexpr (J + 1 < NF) PvStep<J + 1, NF, R>::run(vaddr, lo, hi, p0, p1, pfc, o);
;   }
; template <int DQK, int MODE, bool PIPE>
; DI void attn_core(const u16* __restrict__ Qg, const u16* __restrict__ Kg, const u16* __restrict__ Vtg, int ntiles,
;                   int kr_lo, int rs, int r_q, int c_q, int cs, const float* biasL, char* lds, f32x16 (&o)[4], float& l_out, int tid) {
;     ...
;     if (t + 1 < ntiles) swriteV((t + 1) & 1);
;     if (t + 2 < ntiles) gloadV(t + 2);
;     if (PIPE) {
;       if (t + 1 < ntiles) qk(t + 1, n0, n1);
;       sm_pv(t, c0, c1);
;       if (t + 2 < ntiles) swriteK(t & 1);
;       if (t + 3 < ntiles) gloadK(t + 3);
;     } else {
;       if (is_active(t)) { qk(t, c0, c1); sm_pv(t, c0, c1); }
;       if (t + 1 < ntiles) swriteK((t + 1) & 1);
;       if (t + 2 < ntiles) gloadK(t + 2);
;     }
;     __syncthreads();
	v_mfma_f32_32x32x16_bf16 v[34:49], v[92:95], v[100:103], v[2:17]
	ds_read_b64 v[92:93], v169 offset:0x2220
	ds_read_b64 v[94:95], v169 offset:0x2230
	s_waitcnt lgkmcnt(6)
	v_mfma_f32_32x32x16_bf16 v[2:17], v[96:99], v[100:103], v[2:17]
	ds_read_b64 v[96:97], v169 offset:0x3320
	ds_read_b64 v[98:99], v169 offset:0x3330
	s_waitcnt lgkmcnt(6)
	v_cvt_pk_bf16_f32 v100, v108, v109
	v_cvt_pk_bf16_f32 v101, v110, v111
	v_cvt_pk_bf16_f32 v102, v112, v113
	v_cvt_pk_bf16_f32 v103, v140, v141
	s_nop 1
	v_mfma_f32_32x32x16_bf16 v[66:81], v[28:31], v[100:103], v[66:81]
	ds_read_b64 v[28:29], v169 offset:64
	ds_read_b64 v[30:31], v169 offset:0x50
	s_waitcnt lgkmcnt(6)
	v_mfma_f32_32x32x16_bf16 v[50:65], v[104:107], v[100:103], v[50:65]
	ds_read_b64 v[104:105], v169 offset:0x1140
	ds_read_b64 v[106:107], v169 offset:0x1150
	s_waitcnt lgkmcnt(6)
	v_mfma_f32_32x32x16_bf16 v[34:49], v[92:95], v[100:103], v[34:49]
	ds_read_b64 v[92:93], v169 offset:0x2240
	ds_read_b64 v[94:95], v169 offset:0x2250
	s_waitcnt lgkmcnt(6)
	v_mfma_f32_32x32x16_bf16 v[2:17], v[96:99], v[100:103], v[2:17]
	ds_read_b64 v[96:97], v169 offset:0x3340
	ds_read_b64 v[98:99], v169 offset:0x3350
	s_waitcnt lgkmcnt(6)
	v_cvt_pk_bf16_f32 v100, v146, v147
	v_cvt_pk_bf16_f32 v101, v148, v149
	v_cvt_pk_bf16_f32 v102, v20, v21
	v_cvt_pk_bf16_f32 v103, v24, v25
	s_nop 1
	v_mfma_f32_32x32x16_bf16 v[66:81], v[28:31], v[100:103], v[66:81]
	ds_read_b64 v[28:29], v169 offset:0x60
	ds_read_b64 v[30:31], v169 offset:0x70
	s_waitcnt lgkmcnt(6)
	v_mfma_f32_32x32x16_bf16 v[50:65], v[104:107], v[100:103], v[50:65]
	ds_read_b64 v[104:105], v169 offset:0x1160
	ds_read_b64 v[106:107], v169 offset:0x1170
	s_waitcnt lgkmcnt(6)
	v_mfma_f32_32x32x16_bf16 v[34:49], v[92:95], v[100:103], v[34:49]
	ds_read_b64 v[92:93], v169 offset:0x2260
	ds_read_b64 v[94:95], v169 offset:0x2270
	s_waitcnt lgkmcnt(6)
	v_mfma_f32_32x32x16_bf16 v[2:17], v[96:99], v[100:103], v[2:17]
	ds_read_b64 v[96:97], v169 offset:0x3360
	ds_read_b64 v[98:99], v169 offset:0x3370
	s_waitcnt lgkmcnt(6)
	v_cvt_pk_bf16_f32 v20, v22, v23
	v_cvt_pk_bf16_f32 v21, v26, v27
	v_cvt_pk_bf16_f32 v22, v138, v139
	v_cvt_pk_bf16_f32 v23, v144, v145
	s_nop 1
	v_mfma_f32_32x32x16_bf16 v[66:81], v[28:31], v[20:23], v[66:81]
	s_waitcnt lgkmcnt(4)
	v_mfma_f32_32x32x16_bf16 v[50:65], v[104:107], v[20:23], v[50:65]
	s_waitcnt lgkmcnt(2)
	v_mfma_f32_32x32x16_bf16 v[34:49], v[92:95], v[20:23], v[34:49]
	s_waitcnt lgkmcnt(0)
	v_mfma_f32_32x32x16_bf16 v[2:17], v[96:99], v[20:23], v[2:17]
	s_setprio 0
	s_movk_i32 s14, 0x4000
	v_add_co_u32_e32 v20, vcc, s14, v86
	v_lshl_add_u64 v[160:161], s[6:7], 0, v[158:159]
	s_nop 0
	v_addc_co_u32_e32 v21, vcc, 0, v87, vcc
	global_load_dwordx4 v[138:141], v[20:21], off
	v_readlane_b32 s6, v254, 32
	v_readlane_b32 s7, v254, 33
	v_and_b32_e32 v19, 7, v216
	v_lshl_add_u64 v[20:21], s[0:1], 0, v[90:91]
	v_lshl_add_u64 v[144:145], s[6:7], 0, v[160:161]
	v_lshlrev_b32_e32 v22, 4, v19
	v_mov_b32_e32 v23, v1
	v_readlane_b32 s6, v254, 34
	v_lshl_add_u64 v[20:21], v[20:21], 0, v[22:23]
	v_readlane_b32 s7, v254, 35
	s_mov_b32 s15, 1
	v_mov_b32_e32 v19, v18
	v_lshl_add_u64 v[146:147], s[6:7], 0, v[20:21]
	v_lshl_add_u64 v[20:21], s[0:1], 0, v[88:89]
	v_lshl_add_u64 v[20:21], v[20:21], 0, v[22:23]
	v_lshl_add_u64 v[148:149], s[6:7], 0, v[20:21]
	v_mov_b64_e32 v[150:151], v[148:149]
	v_mov_b64_e32 v[162:163], v[146:147]
	v_mov_b32_e32 v20, v18
	v_mov_b32_e32 v21, v18
	v_mov_b32_e32 v22, v18
	v_mov_b32_e32 v23, v18
	v_mov_b32_e32 v24, v18
	v_mov_b32_e32 v25, v18
	v_mov_b32_e32 v26, v18
	v_mov_b32_e32 v27, v18
	v_mov_b32_e32 v28, v18
	v_mov_b32_e32 v29, v18
	v_mov_b32_e32 v30, v18
	v_mov_b32_e32 v31, v18
	v_mov_b32_e32 v32, v18
	v_mov_b32_e32 v33, v18
	ds_write_b128 v143, v[82:85] offset:43008
	s_waitcnt lgkmcnt(0)
	s_barrier
	s_branch .LBB0_838
.Lmy_back_d1:
	s_mov_b32 s15, s14

; template <int DQK, int MODE, bool PIPE>
; DI void attn_core(const u16* __restrict__ Qg, const u16* __restrict__ Kg, const u16* __restrict__ Vtg, int ntiles,
;                   int kr_lo, int rs, int r_q, int c_q, int cs, const float* biasL, char* lds, f32x16 (&o)[4], float& l_out, int tid) {
;     ...
;     for (int i = 0; i < 16; ++i) { p0[i] = __builtin_amdgcn_exp2f(p0[i]); p1[i] = __builtin_amdgcn_exp2f(p1[i]); ps += p0[i] + p1[i]; }
;     l += ps;
;     ...
;     __syncthreads();
;     ...
;     for (int t = 0; t < ntiles; ++t) step(t, a0, a1, a0, a1);
.LBB0_848:
	v_pk_add_f32 v[236:237], v[82:83], v[98:99]
	v_pk_add_f32 v[236:237], v[236:237], v[84:85]
	v_pk_add_f32 v[236:237], v[236:237], v[86:87]
	v_pk_add_f32 v[236:237], v[236:237], v[88:89]
	v_pk_add_f32 v[236:237], v[236:237], v[90:91]
	v_pk_add_f32 v[236:237], v[236:237], v[92:93]
	v_pk_add_f32 v[236:237], v[236:237], v[94:95]
	v_pk_add_f32 v[236:237], v[236:237], v[96:97]
	v_pk_add_f32 v[236:237], v[236:237], v[100:101]
	v_pk_add_f32 v[236:237], v[236:237], v[102:103]
	v_pk_add_f32 v[236:237], v[236:237], v[104:105]
	v_pk_add_f32 v[236:237], v[236:237], v[106:107]
	v_pk_add_f32 v[236:237], v[236:237], v[108:109]
	v_pk_add_f32 v[236:237], v[236:237], v[110:111]
	v_pk_add_f32 v[236:237], v[236:237], v[112:113]
	v_add_f32_e32 v176, v176, v236
	v_add_f32_e32 v176, v176, v237
	v_lshl_add_u64 v[144:145], v[144:145], 0, s[44:45]
	v_lshl_add_u64 v[162:163], v[162:163], 0, s[2:3]
	s_cmp_lg_u32 s10, s14
	v_lshl_add_u64 v[150:151], v[150:151], 0, s[2:3]
	s_waitcnt lgkmcnt(0)
	s_barrier
	s_cbranch_scc1 .Lmy_back_d1

; #define SBAR() __builtin_amdgcn_sched_barrier(0)
; template <int DQK, int MODE, bool PIPE>
; DI void attn_core(const u16* __restrict__ Qg, const u16* __restrict__ Kg, const u16* __restrict__ Vtg, int ntiles,
;                   int kr_lo, int rs, int r_q, int c_q, int cs, const float* biasL, char* lds, f32x16 (&o)[4], float& l_out, int tid) {
;     ...
;     for (int i = 0; i < 16; ++i) { p0[i] = __builtin_amdgcn_exp2f(p0[i]); p1[i] = __builtin_amdgcn_exp2f(p1[i]); ps += p0[i] + p1[i]; }
;     l += ps;
;     const char* vb = lds + (t & 1) * A_BUF + A_VOFF + r32 * 136 + h * 8;
;     {
;       bf16x8 pfc;
;       constexpr int R = PV_RING;
;       const unsigned vaddr = (unsigned)(size_t)vb;
;       s16x4 vlo[R], vhi[R];
;       SBAR();
;       vlo[0] = lds_rd64<0>(vaddr); vhi[0] = lds_rd64<16>(vaddr);
;       vlo[1] = lds_rd64<32 * 136>(vaddr); vhi[1] = lds_rd64<32 * 136 + 16>(vaddr);
;       if (R > 2) { vlo[2 % R] = lds_rd64<64 * 136>(vaddr); vhi[2 % R] = lds_rd64<64 * 136 + 16>(vaddr); }
;       if (R > 3) { vlo[3 % R] = lds_rd64<96 * 136>(vaddr); vhi[3 % R] = lds_rd64<96 * 136 + 16>(vaddr); }
;       SBAR();
;       __builtin_amdgcn_s_setprio(1);
;       PvStep<0, 16, R>::run(vaddr, vlo, vhi, p0, p1, pfc, o);
;       __builtin_amdgcn_s_setprio(0);
;     ...
;     if (t + 1 < ntiles) swriteV((t + 1) & 1);
;     if (t + 2 < ntiles) gloadV(t + 2);
;     if (PIPE) {
;       if (t + 1 < ntiles) qk(t + 1, n0, n1);
;       sm_pv(t, c0, c1);
;       if (t + 2 < ntiles) swriteK(t & 1);
;       if (t + 3 < ntiles) gloadK(t + 3);
;     } else {
;       if (is_active(t)) { qk(t, c0, c1); sm_pv(t, c0, c1); }
;       if (t + 1 < ntiles) swriteK((t + 1) & 1);
;       if (t + 2 < ntiles) gloadK(t + 2);
;     }
;     __syncthreads();
.LBB0_853:
	v_exp_f32_e32 v35, v18
	v_exp_f32_e32 v138, v36
	v_exp_f32_e32 v56, v19
	v_exp_f32_e32 v139, v37
	v_exp_f32_e32 v57, v20
	v_exp_f32_e32 v140, v38
	v_exp_f32_e32 v58, v21
	v_exp_f32_e32 v141, v39
	v_add_f32_e32 v18, v138, v35
	v_add_f32_e32 v18, 0, v18
	v_add_f32_e32 v19, v139, v56
	v_add_f32_e32 v18, v19, v18
	v_add_f32_e32 v19, v140, v57
	v_add_f32_e32 v18, v19, v18
	v_add_f32_e32 v19, v141, v58
	v_add_f32_e32 v36, v19, v18
	v_exp_f32_e32 v19, v22
	v_exp_f32_e32 v21, v40
	v_exp_f32_e32 v18, v23
	v_exp_f32_e32 v20, v41
	v_lshlrev_b32_e32 v145, 2, v195
	v_mov_b32_e32 v3, v2
	v_pk_mov_b32 v[52:53], v[18:19], v[18:19] op_sel:[1,0]
	v_pk_add_f32 v[22:23], v[20:21], v[18:19]
	v_exp_f32_e32 v19, v24
	v_add_f32_e32 v23, v23, v36
	v_pk_mov_b32 v[36:37], v[20:21], v[20:21] op_sel:[1,0]
	v_exp_f32_e32 v21, v42
	v_exp_f32_e32 v18, v25
	v_exp_f32_e32 v20, v43
	v_add_f32_e32 v38, v22, v23
	v_mov_b32_e32 v4, v2
	v_pk_mov_b32 v[54:55], v[18:19], v[18:19] op_sel:[1,0]
	v_pk_add_f32 v[22:23], v[20:21], v[18:19]
	v_pk_mov_b32 v[40:41], v[20:21], v[20:21] op_sel:[1,0]
	v_exp_f32_e32 v19, v26
	v_exp_f32_e32 v21, v44
	v_exp_f32_e32 v18, v27
	v_exp_f32_e32 v20, v45
	v_add_f32_e32 v23, v23, v38
	v_add_f32_e32 v24, v22, v23
	v_pk_mov_b32 v[104:105], v[18:19], v[18:19] op_sel:[1,0]
	v_pk_add_f32 v[22:23], v[20:21], v[18:19]
	v_pk_mov_b32 v[38:39], v[20:21], v[20:21] op_sel:[1,0]
	v_exp_f32_e32 v19, v28
	v_exp_f32_e32 v21, v46
	v_exp_f32_e32 v18, v29
	v_exp_f32_e32 v20, v47
	v_add_f32_e32 v23, v23, v24
	v_add_f32_e32 v24, v22, v23
	v_pk_mov_b32 v[106:107], v[18:19], v[18:19] op_sel:[1,0]
	v_pk_add_f32 v[22:23], v[20:21], v[18:19]
	v_pk_mov_b32 v[42:43], v[20:21], v[20:21] op_sel:[1,0]
	v_exp_f32_e32 v19, v30
	v_exp_f32_e32 v21, v48
	v_exp_f32_e32 v18, v31
	v_exp_f32_e32 v20, v49
	v_add_f32_e32 v23, v23, v24
	v_add_f32_e32 v24, v22, v23
	v_pk_mov_b32 v[48:49], v[18:19], v[18:19] op_sel:[1,0]
	v_pk_add_f32 v[22:23], v[20:21], v[18:19]
	v_pk_mov_b32 v[108:109], v[20:21], v[20:21] op_sel:[1,0]
	v_exp_f32_e32 v19, v32
	v_exp_f32_e32 v21, v50
	v_exp_f32_e32 v18, v33
	v_exp_f32_e32 v20, v51
	v_add_f32_e32 v23, v23, v24
	v_add_f32_e32 v24, v22, v23
	v_pk_mov_b32 v[110:111], v[18:19], v[18:19] op_sel:[1,0]
	v_pk_add_f32 v[22:23], v[20:21], v[18:19]
	v_mov_b32_e32 v5, v2
	v_add_f32_e32 v23, v23, v24
	v_add_f32_e32 v18, v22, v23
	v_mov_b32_e32 v6, v2
	v_mov_b32_e32 v7, v2
	v_mov_b32_e32 v8, v2
	v_mov_b32_e32 v9, v2
	v_mov_b32_e32 v10, v2
	v_mov_b32_e32 v11, v2
	v_mov_b32_e32 v12, v2
	v_mov_b32_e32 v13, v2
	v_mov_b32_e32 v14, v2
	v_mov_b32_e32 v15, v2
	v_mov_b32_e32 v16, v2
	v_mov_b32_e32 v17, v2
	v_add_f32_e32 v155, v2, v18
	v_pk_mov_b32 v[112:113], v[20:21], v[20:21] op_sel:[1,0]
	ds_read_b64 v[18:19], v169 offset:0
	ds_read_b64 v[20:21], v169 offset:16
	ds_read_b64 v[22:23], v169 offset:0x1100
	ds_read_b64 v[24:25], v169 offset:0x1110
	ds_read_b64 v[44:45], v169 offset:0x2200
	ds_read_b64 v[46:47], v169 offset:0x2210
	ds_read_b64 v[88:89], v169 offset:0x3300
	ds_read_b64 v[90:91], v169 offset:0x3310
	s_setprio 1
	s_waitcnt lgkmcnt(6)
	v_cvt_pk_bf16_f32 v92, v35, v56
	v_cvt_pk_bf16_f32 v93, v57, v58
	v_cvt_pk_bf16_f32 v94, v52, v53
	v_cvt_pk_bf16_f32 v95, v54, v55
	s_nop 1
	v_mfma_f32_32x32x16_bf16 v[66:81], v[18:21], v[92:95], v[2:17]
	ds_read_b64 v[96:97], v169 offset:32
	ds_read_b64 v[98:99], v169 offset:48
	s_waitcnt lgkmcnt(6)
	v_mfma_f32_32x32x16_bf16 v[50:65], v[22:25], v[92:95], v[2:17]
	ds_read_b64 v[100:101], v169 offset:0x1120
	ds_read_b64 v[102:103], v169 offset:0x1130
	s_waitcnt lgkmcnt(6)
	v_mfma_f32_32x32x16_bf16 v[18:33], v[44:47], v[92:95], v[2:17]
	ds_read_b64 v[44:45], v169 offset:0x2220
	ds_read_b64 v[46:47], v169 offset:0x2230
	s_waitcnt lgkmcnt(6)
	v_mfma_f32_32x32x16_bf16 v[2:17], v[88:91], v[92:95], v[2:17]
	ds_read_b64 v[88:89], v169 offset:0x3320
	ds_read_b64 v[90:91], v169 offset:0x3330
	s_waitcnt lgkmcnt(6)
	v_cvt_pk_bf16_f32 v92, v104, v105
	v_cvt_pk_bf16_f32 v93, v106, v107
	v_cvt_pk_bf16_f32 v94, v48, v49
	v_cvt_pk_bf16_f32 v95, v110, v111
	s_nop 1
	v_mfma_f32_32x32x16_bf16 v[66:81], v[96:99], v[92:95], v[66:81]
	ds_read_b64 v[96:97], v169 offset:64
	ds_read_b64 v[98:99], v169 offset:0x50
	s_waitcnt lgkmcnt(6)
	v_mfma_f32_32x32x16_bf16 v[50:65], v[100:103], v[92:95], v[50:65]
	ds_read_b64 v[100:101], v169 offset:0x1140
	ds_read_b64 v[102:103], v169 offset:0x1150
	s_waitcnt lgkmcnt(6)
	v_mfma_f32_32x32x16_bf16 v[18:33], v[44:47], v[92:95], v[18:33]
	ds_read_b64 v[44:45], v169 offset:0x2240
	ds_read_b64 v[46:47], v169 offset:0x2250
	s_waitcnt lgkmcnt(6)
	v_mfma_f32_32x32x16_bf16 v[2:17], v[88:91], v[92:95], v[2:17]
	ds_read_b64 v[88:89], v169 offset:0x3340
	ds_read_b64 v[90:91], v169 offset:0x3350
	s_waitcnt lgkmcnt(6)
	v_cvt_pk_bf16_f32 v92, v138, v139
	v_cvt_pk_bf16_f32 v93, v140, v141
	v_cvt_pk_bf16_f32 v94, v36, v37
	v_cvt_pk_bf16_f32 v95, v40, v41
	s_nop 1
	v_mfma_f32_32x32x16_bf16 v[66:81], v[96:99], v[92:95], v[66:81]
	ds_read_b64 v[96:97], v169 offset:0x60
	ds_read_b64 v[98:99], v169 offset:0x70
	s_waitcnt lgkmcnt(6)
	v_mfma_f32_32x32x16_bf16 v[50:65], v[100:103], v[92:95], v[50:65]
	ds_read_b64 v[100:101], v169 offset:0x1160
	ds_read_b64 v[102:103], v169 offset:0x1170
	s_waitcnt lgkmcnt(6)
	v_mfma_f32_32x32x16_bf16 v[18:33], v[44:47], v[92:95], v[18:33]
	ds_read_b64 v[44:45], v169 offset:0x2260
	ds_read_b64 v[46:47], v169 offset:0x2270
	s_waitcnt lgkmcnt(6)
	v_mfma_f32_32x32x16_bf16 v[2:17], v[88:91], v[92:95], v[2:17]
	ds_read_b64 v[88:89], v169 offset:0x3360
	ds_read_b64 v[90:91], v169 offset:0x3370
	s_waitcnt lgkmcnt(6)
	v_cvt_pk_bf16_f32 v36, v38, v39
	v_cvt_pk_bf16_f32 v37, v42, v43
	v_cvt_pk_bf16_f32 v38, v108, v109
	v_cvt_pk_bf16_f32 v39, v112, v113
	s_nop 1
	v_mfma_f32_32x32x16_bf16 v[66:81], v[96:99], v[36:39], v[66:81]
	s_waitcnt lgkmcnt(4)
	v_mfma_f32_32x32x16_bf16 v[50:65], v[100:103], v[36:39], v[50:65]
	s_waitcnt lgkmcnt(2)
	v_mfma_f32_32x32x16_bf16 v[18:33], v[44:47], v[36:39], v[18:33]
	s_waitcnt lgkmcnt(0)
	v_mfma_f32_32x32x16_bf16 v[2:17], v[88:91], v[36:39], v[2:17]
	s_setprio 0
	v_add_co_u32_e32 v36, vcc, 0x4000, v86
	v_readlane_b32 s0, v254, 36
	s_nop 0
	v_addc_co_u32_e32 v37, vcc, 0, v87, vcc
	global_load_dwordx4 v[138:141], v[36:37], off
	v_readlane_b32 s1, v254, 37
	s_waitcnt vmcnt(3)
	ds_write_b128 v143, v[82:85] offset:43008
	s_waitcnt lgkmcnt(0)
	s_barrier
	v_lshl_add_u64 v[152:153], s[0:1], 0, v[160:161]
	s_mov_b32 s12, 1
	v_mov_b32_e32 v35, v34
	v_mov_b32_e32 v36, v34
	v_mov_b32_e32 v37, v34
	v_mov_b32_e32 v38, v34
	v_mov_b32_e32 v39, v34
	v_mov_b32_e32 v40, v34
	v_mov_b32_e32 v41, v34
	v_mov_b32_e32 v42, v34
	v_mov_b32_e32 v43, v34
	v_mov_b32_e32 v44, v34
	v_mov_b32_e32 v45, v34
	v_mov_b32_e32 v46, v34
	v_mov_b32_e32 v47, v34
	v_mov_b32_e32 v48, v34
	v_mov_b32_e32 v49, v34
	s_branch .LBB0_854
.Lmy_back_d2:
	s_mov_b32 s12, s11

; template <int DQK, int MODE, bool PIPE>
; DI void attn_core(const u16* __restrict__ Qg, const u16* __restrict__ Kg, const u16* __restrict__ Vtg, int ntiles,
;                   int kr_lo, int rs, int r_q, int c_q, int cs, const float* biasL, char* lds, f32x16 (&o)[4], float& l_out, int tid) {
;     ...
;     for (int i = 0; i < 16; ++i) { p0[i] = __builtin_amdgcn_exp2f(p0[i]); p1[i] = __builtin_amdgcn_exp2f(p1[i]); ps += p0[i] + p1[i]; }
;     l += ps;
;     ...
;     __syncthreads();
;     ...
;     for (int t = 0; t < ntiles; ++t) step(t, a0, a1, a0, a1);
.LBB0_864:
	v_pk_add_f32 v[236:237], v[82:83], v[98:99]
	v_pk_add_f32 v[236:237], v[236:237], v[84:85]
	v_pk_add_f32 v[236:237], v[236:237], v[86:87]
	v_pk_add_f32 v[236:237], v[236:237], v[88:89]
	v_pk_add_f32 v[236:237], v[236:237], v[90:91]
	v_pk_add_f32 v[236:237], v[236:237], v[92:93]
	v_pk_add_f32 v[236:237], v[236:237], v[94:95]
	v_pk_add_f32 v[236:237], v[236:237], v[96:97]
	v_pk_add_f32 v[236:237], v[236:237], v[100:101]
	v_pk_add_f32 v[236:237], v[236:237], v[102:103]
	v_pk_add_f32 v[236:237], v[236:237], v[104:105]
	v_pk_add_f32 v[236:237], v[236:237], v[106:107]
	v_pk_add_f32 v[236:237], v[236:237], v[108:109]
	v_pk_add_f32 v[236:237], v[236:237], v[110:111]
	v_pk_add_f32 v[236:237], v[236:237], v[112:113]
	v_add_f32_e32 v155, v155, v236
	v_add_f32_e32 v155, v155, v237
	v_lshl_add_u64 v[152:153], v[152:153], 0, s[44:45]
	v_lshl_add_u64 v[146:147], v[146:147], 0, s[2:3]
	s_cmp_lg_u32 s10, s11
	v_lshl_add_u64 v[148:149], v[148:149], 0, s[2:3]
	s_waitcnt lgkmcnt(0)
	s_barrier
	s_cbranch_scc1 .Lmy_back_d2
